# even-mixer elementwise loop: conv weight, gate row and rotary-input loads hoisted to the top of the row iteration (3 of 6 serialized round trips removed)
# speedup vs baseline: 1.0011x; 1.0011x over previous
; __device__ __forceinline__ float lo2f(unsigned u) { return __uint_as_float(u << 16); }
; __device__ __forceinline__ float hi2f(unsigned u) { return __uint_as_float(u & 0xffff0000u); }
; __device__ void phase_even_elem(const Params& p, const bf16_t* P, bf16_t* CAT, bf16_t* Kall) {
;     ...
;   for (int r = blockIdx.x * 8 + wave; r < M_ALL; r += gridDim.x * 8) {
;     int b, key; row_bk(r, b, key);
;     const bool latent = r >= NCTX;
;     const int t = latent ? ((r - NCTX) & 8191) : (r & 255), T = latent ? 8192 : 256;
;     const int c0 = lane * 8;
;     float cv[3][8];
; #pragma unroll
;     for (int dt = 0; dt < 3; ++dt) {
;       const int tt = t + dt - 1;
;       if (tt >= 0 && tt < T) {
;         const bf16_t* pr = P + (size_t)(r + dt - 1) * 2048;
;         u32x4 gc = *(const u32x4*)(pr + 512 + c0), vv = *(const u32x4*)(pr + 1024 + c0);
; #pragma unroll
;         for (int e = 0; e < 4; ++e) { cv[dt][2 * e] = lo2f(gc[e]) * lo2f(vv[e]); cv[dt][2 * e + 1] = hi2f(gc[e]) * hi2f(vv[e]); }
;       } else {
; #pragma unroll
;         for (int e = 0; e < 8; ++e) cv[dt][e] = 0.f;
;       }
;     }
.LBB0_1163:
	global_load_dwordx4 v[82:85], v[6:7], off offset:2048
	global_load_dwordx4 v[86:89], v[6:7], off offset:2064
	global_load_dwordx4 v[90:93], v[6:7], off
	global_load_dwordx4 v[94:97], v[6:7], off offset:16
	global_load_dwordx4 v[98:101], v[8:9], off offset:16
	global_load_dwordx4 v[102:105], v[8:9], off
	v_ashrrev_i32_e32 v107, 31, v0
	v_mov_b32_e32 v106, v0
	v_lshlrev_b64 v[106:107], 12, v[106:107]
	v_lshl_add_u64 v[112:113], s[20:21], 0, v[106:107]
	v_lshl_add_u64 v[106:107], v[112:113], 0, v[2:3]
	global_load_dwordx4 v[108:111], v[106:107], off
	v_mov_b32_e32 v115, v3
	v_mov_b32_e32 v114, v16
	v_lshl_add_u64 v[112:113], v[112:113], 0, v[114:115]
	global_load_ushort v116, v[112:113], off offset:3840
	v_cmp_lt_i32_e64 s[8:9], s3, v0
	v_and_b32_e32 v1, 0xff, v0
	s_and_saveexec_b64 s[0:1], s[8:9]
	s_xor_b64 s[0:1], exec, s[0:1]
	v_add_u32_e32 v1, 0xfffffc00, v0
	v_lshrrev_b32_e32 v19, 13, v1
	v_and_b32_e32 v1, 0x1fff, v1
	v_add_u32_e32 v18, 0x100, v1
	v_and_b32_e32 v1, 0xff, v0
	s_andn2_saveexec_b64 s[0:1], s[0:1]
	v_ashrrev_i32_e32 v19, 8, v0
	v_mov_b32_e32 v18, v1
	s_or_b64 exec, exec, s[0:1]
	s_waitcnt lgkmcnt(0)
	v_add_u32_e32 v17, 0x1c00, v0
	v_and_b32_e32 v48, 0x1fff, v17
	v_cmp_lt_i32_e64 s[8:9], s3, v0
	v_mov_b32_e32 v24, 0
	v_mov_b32_e32 v20, 0
	v_cndmask_b32_e64 v36, v1, v48, s[8:9]
	v_cndmask_b32_e64 v17, v45, v46, s[8:9]
	v_add_u32_e32 v1, -1, v36
	v_cmp_lt_u32_e64 s[10:11], v1, v17
	v_mov_b32_e32 v21, 0
	v_mov_b32_e32 v22, 0
	v_mov_b32_e32 v23, 0
	v_mov_b32_e32 v26, 0
	v_mov_b32_e32 v27, 0
	v_mov_b32_e32 v28, 0
	v_mov_b32_e32 v29, 0
	s_and_saveexec_b64 s[0:1], s[10:11]
	s_cbranch_execz .LBB0_1169
	v_add_u32_e32 v20, -1, v0
	v_ashrrev_i32_e32 v21, 31, v20
	v_lshlrev_b64 v[20:21], 12, v[20:21]
	v_lshl_add_u64 v[30:31], v[12:13], 0, v[20:21]
	global_load_dwordx4 v[20:23], v[30:31], off offset:1024
	global_load_dwordx4 v[26:29], v[30:31], off offset:2048
	s_waitcnt vmcnt(0)
	v_lshlrev_b32_e32 v30, 16, v20
	v_and_b32_e32 v31, 0xffff0000, v20
	v_lshlrev_b32_e32 v32, 16, v26
	v_and_b32_e32 v33, 0xffff0000, v26
	v_lshlrev_b32_e32 v20, 16, v21
	v_and_b32_e32 v21, 0xffff0000, v21
	v_lshlrev_b32_e32 v26, 16, v27
	v_and_b32_e32 v27, 0xffff0000, v27
	v_lshlrev_b32_e32 v34, 16, v22
	v_and_b32_e32 v35, 0xffff0000, v22
	v_lshlrev_b32_e32 v38, 16, v28
	v_and_b32_e32 v39, 0xffff0000, v28
	v_lshlrev_b32_e32 v40, 16, v23
	v_and_b32_e32 v41, 0xffff0000, v23
	v_lshlrev_b32_e32 v42, 16, v29
	v_and_b32_e32 v43, 0xffff0000, v29
	v_pk_mul_f32 v[28:29], v[30:31], v[32:33]
	v_pk_mul_f32 v[26:27], v[20:21], v[26:27]
	v_pk_mul_f32 v[22:23], v[34:35], v[38:39]
	v_pk_mul_f32 v[20:21], v[40:41], v[42:43]

; __device__ __forceinline__ float bf2f(bf16_t v) { return __uint_as_float(((unsigned)v) << 16); }
; __device__ __forceinline__ unsigned pk2(float lo, float hi) { f32x2 v = {lo, hi}; return __builtin_bit_cast(unsigned, __builtin_convertvector(v, bf16v2)); }
; __device__ __forceinline__ float lo2f(unsigned u) { return __uint_as_float(u << 16); }
; __device__ __forceinline__ float hi2f(unsigned u) { return __uint_as_float(u & 0xffff0000u); }
; __device__ void phase_even_elem(const Params& p, const bf16_t* P, bf16_t* CAT, bf16_t* Kall) {
;     ...
;     u32x4 gb = *(const u32x4*)(P + (size_t)r * 2048 + c0);
;     float o[8];
; #pragma unroll
;     for (int e = 0; e < 8; ++e) {
;       const float w0 = p.even_conv_w[c0 + e], w1 = p.even_conv_w[512 + c0 + e], w2 = p.even_conv_w[1024 + c0 + e];
;       const float g = (e & 1) ? hi2f(gb[e >> 1]) : lo2f(gb[e >> 1]);
;       o[e] = g * (cv[0][e] * w0 + cv[1][e] * w1 + cv[2][e] * w2);
;     }
;     u32x4 ov; ov.x = pk2(o[0], o[1]); ov.y = pk2(o[2], o[3]); ov.z = pk2(o[4], o[5]); ov.w = pk2(o[6], o[7]);
;     *(u32x4*)(CAT + (size_t)r * DM + c0) = ov;
;     {
;       const int d = lane & 31;
;       float v = bf2f(P[(size_t)r * 2048 + 1920 + d]);
;       const float pv = __shfl_xor(v, 8);
;       const int idx = d & 15, fi = idx & 7;
;       if (latent) {
;         const float* rp = p.rope + ((size_t)t * 2 + (d >> 4)) * 16 + fi;
;         const float cs = rp[0], sn = rp[8];
;         v = (idx < 8) ? (v * cs - pv * sn) : (pv * sn + v * cs);
;       }
.LBB0_1173:
	s_or_b64 exec, exec, s[0:1]
	v_lshlrev_b64 v[74:75], 12, v[0:1]
	v_lshl_add_u64 v[78:79], s[20:21], 0, v[74:75]
	v_lshl_add_u64 v[74:75], v[78:79], 0, v[2:3]
	s_waitcnt vmcnt(0)
	v_lshlrev_b64 v[80:81], 11, v[0:1]
	v_mov_b32_e32 v17, v3
	v_lshl_add_u64 v[80:81], v[4:5], 0, v[80:81]
	v_pk_mul_f32 v[34:35], v[34:35], v[82:83]
	v_pk_mul_f32 v[32:33], v[32:33], v[84:85]
	v_pk_mul_f32 v[30:31], v[30:31], v[86:87]
	v_pk_mul_f32 v[24:25], v[24:25], v[88:89]
	v_pk_fma_f32 v[28:29], v[28:29], v[90:91], v[34:35]
	v_pk_fma_f32 v[26:27], v[26:27], v[92:93], v[32:33]
	v_pk_fma_f32 v[22:23], v[22:23], v[94:95], v[30:31]
	v_pk_fma_f32 v[20:21], v[20:21], v[96:97], v[24:25]
	v_pk_fma_f32 v[24:25], v[36:37], v[102:103], v[28:29]
	v_pk_fma_f32 v[26:27], v[38:39], v[104:105], v[26:27]
	v_pk_fma_f32 v[22:23], v[40:41], v[98:99], v[22:23]
	v_pk_fma_f32 v[20:21], v[42:43], v[100:101], v[20:21]
	s_waitcnt vmcnt(0)
	v_lshlrev_b32_e32 v28, 16, v108
	v_and_b32_e32 v29, 0xffff0000, v108
	v_lshlrev_b32_e32 v30, 16, v109
	v_and_b32_e32 v31, 0xffff0000, v109
	v_lshlrev_b32_e32 v32, 16, v110
	v_and_b32_e32 v33, 0xffff0000, v110
	v_lshlrev_b32_e32 v34, 16, v111
	v_and_b32_e32 v35, 0xffff0000, v111
	v_pk_mul_f32 v[24:25], v[24:25], v[28:29]
	v_pk_mul_f32 v[26:27], v[26:27], v[30:31]
	v_pk_mul_f32 v[22:23], v[22:23], v[32:33]
	v_pk_mul_f32 v[28:29], v[20:21], v[34:35]
	v_cvt_pk_bf16_f32 v20, v24, v25
	v_cvt_pk_bf16_f32 v21, v26, v27
	v_cvt_pk_bf16_f32 v22, v22, v23
	v_cvt_pk_bf16_f32 v23, v28, v29
	global_store_dwordx4 v[80:81], v[20:23], off
	s_nop 1
	v_lshl_add_u64 v[20:21], v[78:79], 0, v[16:17]
	s_waitcnt vmcnt(0)
	v_lshlrev_b32_e32 v1, 16, v116
	ds_bpermute_b32 v17, v44, v1
	s_and_saveexec_b64 s[0:1], s[8:9]
	s_cbranch_execz .LBB0_1175
	v_lshl_or_b32 v20, v48, 7, v47
	v_mov_b32_e32 v21, v3
	v_lshl_add_u64 v[20:21], v[10:11], 0, v[20:21]
	global_load_dword v22, v[20:21], off offset:32
	global_load_dword v23, v[20:21], off
	s_waitcnt vmcnt(1) lgkmcnt(0)
	v_mul_f32_e32 v17, v22, v17
	v_cndmask_b32_e64 v17, v17, -v17, vcc
	s_waitcnt vmcnt(0)
	v_fmac_f32_e32 v17, v23, v1
	v_mov_b32_e32 v1, v17
